# fused LRU gate loop with next-pass loads prefetched one pass ahead
# baseline (speedup 1.0000x reference)
.Lgate_go:
	v_add_u32_e32 v1, s20, v1
	v_lshlrev_b32_e32 v2, 3, v1
	s_mov_b32 s19, 16
	v_ashrrev_i32_e32 v12, 7, v1
	v_ashrrev_i32_e32 v13, 31, v12
	v_and_b32_e32 v3, 0x3f8, v2
	v_lshlrev_b64 v[16:17], 11, v[12:13]
	v_lshlrev_b64 v[12:13], 12, v[12:13]
	v_lshlrev_b32_e32 v18, 1, v3
	v_mov_b32_e32 v19, v0
	v_lshl_add_u64 v[76:77], s[10:11], 0, v[12:13]
	v_lshl_add_u64 v[76:77], v[76:77], 0, v[18:19]
	v_lshl_add_u64 v[78:79], s[6:7], 0, v[16:17]
	v_lshl_add_u64 v[78:79], v[78:79], 0, v[18:19]
	v_lshl_add_u64 v[80:81], s[8:9], 0, v[16:17]
	v_lshl_add_u64 v[80:81], v[80:81], 0, v[18:19]
	global_load_dwordx4 v[64:67], v[76:77], off
	global_load_dwordx4 v[68:71], v[78:79], off
	global_load_dwordx4 v[72:75], v[80:81], off
	s_lshl_b32 s38, s18, 5
	s_mov_b32 s39, 0
	s_lshl_b32 s40, s18, 4
	s_mov_b32 s41, 0
	v_lshl_add_u64 v[76:77], v[76:77], 0, s[38:39]
	v_lshl_add_u64 v[78:79], v[78:79], 0, s[40:41]
	v_lshl_add_u64 v[80:81], v[80:81], 0, s[40:41]
	s_waitcnt vmcnt(0)
.LBB0_363:
	s_waitcnt vmcnt(1)
	v_ashrrev_i32_e32 v12, 7, v1
	v_ashrrev_i32_e32 v13, 31, v12
	v_and_b32_e32 v3, 0x3f8, v2
	v_lshlrev_b64 v[16:17], 11, v[12:13]
	v_lshlrev_b32_e32 v18, 1, v3
	v_mov_b32_e32 v19, v0
	v_mov_b32_e32 v12, v64
	v_mov_b32_e32 v13, v65
	v_mov_b32_e32 v14, v66
	v_mov_b32_e32 v15, v67
	v_mov_b32_e32 v4, v68
	v_mov_b32_e32 v5, v69
	v_mov_b32_e32 v6, v70
	v_mov_b32_e32 v7, v71
	v_mov_b32_e32 v8, v72
	v_mov_b32_e32 v9, v73
	v_mov_b32_e32 v10, v74
	v_mov_b32_e32 v11, v75
	s_cmp_eq_u32 s19, 1
	s_cbranch_scc1 .Lgate_nopf
	global_load_dwordx4 v[64:67], v[76:77], off
	v_lshl_add_u64 v[76:77], v[76:77], 0, s[38:39]
	global_load_dwordx4 v[68:71], v[78:79], off
	v_lshl_add_u64 v[78:79], v[78:79], 0, s[40:41]
	global_load_dwordx4 v[72:75], v[80:81], off
	v_lshl_add_u64 v[80:81], v[80:81], 0, s[40:41]
.Lgate_nopf:
	v_add_u32_e32 v1, s18, v1
	v_lshlrev_b32_e32 v24, 16, v12
	v_mul_f32_e32 v3, 0x3d372713, v24
	v_lshlrev_b32_e32 v20, 16, v4
	v_and_b32_e32 v21, 0xffff0000, v4
	v_mul_f32_e32 v3, v3, v24
	v_mov_b32_e32 v4, v24
	v_fmac_f32_e32 v4, v3, v4
	v_mul_f32_e32 v3, 0x3f4c422a, v4
	v_mul_f32_e32 v3, -2.0, v3
	v_mul_f32_e32 v3, 0x3fb8aa3b, v3
	v_exp_f32_e32 v3, v3
	v_and_b32_e32 v25, 0xffff0000, v12
	v_mov_b32_e32 v4, v25
	v_lshlrev_b32_e32 v22, 16, v8
	v_add_f32_e32 v3, 1.0, v3
	v_rcp_f32_e32 v26, v3
	v_mul_f32_e32 v3, 0x3d372713, v25
	v_mul_f32_e32 v3, v3, v25
	v_fmac_f32_e32 v4, v3, v4
	v_mul_f32_e32 v3, 0x3f4c422a, v4
	v_mul_f32_e32 v3, -2.0, v3
	v_mul_f32_e32 v3, 0x3fb8aa3b, v3
	v_exp_f32_e32 v3, v3
	v_and_b32_e32 v23, 0xffff0000, v8
	v_lshlrev_b32_e32 v12, 16, v13
	v_pk_add_f32 v[20:21], v[20:21], v[22:23]
	v_add_f32_e32 v3, 1.0, v3
	v_rcp_f32_e32 v27, v3
	v_mul_f32_e32 v3, 0x3d372713, v12
	v_mul_f32_e32 v3, v3, v12
	v_and_b32_e32 v13, 0xffff0000, v13
	v_pk_mul_f32 v[22:23], v[26:27], v[24:25]
	v_lshlrev_b32_e32 v4, 16, v5
	v_pk_mul_f32 v[20:21], v[20:21], v[22:23]
	v_mov_b32_e32 v22, v12
	v_fmac_f32_e32 v22, v3, v22
	v_mul_f32_e32 v3, 0x3f4c422a, v22
	v_mul_f32_e32 v3, -2.0, v3
	v_mul_f32_e32 v3, 0x3fb8aa3b, v3
	v_exp_f32_e32 v3, v3
	v_and_b32_e32 v5, 0xffff0000, v5
	v_lshlrev_b32_e32 v8, 16, v9
	v_and_b32_e32 v9, 0xffff0000, v9
	v_add_f32_e32 v3, 1.0, v3
	v_rcp_f32_e32 v22, v3
	v_mul_f32_e32 v3, 0x3d372713, v13
	v_pk_add_f32 v[4:5], v[4:5], v[8:9]
	v_mul_f32_e32 v3, v3, v13
	v_mov_b32_e32 v8, v13
	v_fmac_f32_e32 v8, v3, v8
	v_mul_f32_e32 v3, 0x3f4c422a, v8
	v_mul_f32_e32 v3, -2.0, v3
	v_mul_f32_e32 v3, 0x3fb8aa3b, v3
	v_exp_f32_e32 v3, v3
	s_nop 0
	v_add_f32_e32 v3, 1.0, v3
	v_rcp_f32_e32 v23, v3
	s_nop 0
	v_pk_mul_f32 v[8:9], v[22:23], v[12:13]
	v_lshlrev_b32_e32 v22, 16, v14
	v_mul_f32_e32 v3, 0x3d372713, v22
	v_pk_mul_f32 v[8:9], v[4:5], v[8:9]
	v_lshlrev_b32_e32 v4, 16, v6
	v_and_b32_e32 v5, 0xffff0000, v6
	v_mul_f32_e32 v3, v3, v22
	v_mov_b32_e32 v6, v22
	v_fmac_f32_e32 v6, v3, v6
	v_mul_f32_e32 v3, 0x3f4c422a, v6
	v_mul_f32_e32 v3, -2.0, v3
	v_mul_f32_e32 v3, 0x3fb8aa3b, v3
	v_exp_f32_e32 v3, v3
	v_and_b32_e32 v23, 0xffff0000, v14
	v_mov_b32_e32 v6, v23
	v_lshlrev_b32_e32 v12, 16, v10
	v_add_f32_e32 v3, 1.0, v3
	v_rcp_f32_e32 v24, v3
	v_mul_f32_e32 v3, 0x3d372713, v23
	v_mul_f32_e32 v3, v3, v23
	v_fmac_f32_e32 v6, v3, v6
	v_mul_f32_e32 v3, 0x3f4c422a, v6
	v_mul_f32_e32 v3, -2.0, v3
	v_mul_f32_e32 v3, 0x3fb8aa3b, v3
	v_exp_f32_e32 v3, v3
	v_and_b32_e32 v13, 0xffff0000, v10
	v_lshlrev_b32_e32 v10, 16, v15
	v_mov_b32_e32 v14, v10
	v_add_f32_e32 v3, 1.0, v3
	v_rcp_f32_e32 v25, v3
	v_mul_f32_e32 v3, 0x3d372713, v10
	v_mul_f32_e32 v3, v3, v10
	v_fmac_f32_e32 v14, v3, v14
	v_mul_f32_e32 v3, 0x3f4c422a, v14
	v_mul_f32_e32 v3, -2.0, v3
	v_mul_f32_e32 v3, 0x3fb8aa3b, v3
	v_exp_f32_e32 v3, v3
	v_pk_add_f32 v[4:5], v[4:5], v[12:13]
	v_pk_mul_f32 v[12:13], v[24:25], v[22:23]
	v_lshlrev_b32_e32 v6, 16, v11
	v_pk_mul_f32 v[12:13], v[4:5], v[12:13]
	v_lshlrev_b32_e32 v4, 16, v7
	v_and_b32_e32 v5, 0xffff0000, v7
	v_and_b32_e32 v7, 0xffff0000, v11
	v_and_b32_e32 v11, 0xffff0000, v15
	v_add_f32_e32 v3, 1.0, v3
	v_rcp_f32_e32 v14, v3
	v_mul_f32_e32 v3, 0x3d372713, v11
	v_pk_add_f32 v[4:5], v[4:5], v[6:7]
	v_mul_f32_e32 v3, v3, v11
	v_mov_b32_e32 v6, v11
	v_fmac_f32_e32 v6, v3, v6
	v_mul_f32_e32 v3, 0x3f4c422a, v6
	v_mul_f32_e32 v3, -2.0, v3
	v_mul_f32_e32 v3, 0x3fb8aa3b, v3
	v_exp_f32_e32 v3, v3
	s_nop 0
	v_add_f32_e32 v3, 1.0, v3
	v_rcp_f32_e32 v15, v3
	s_nop 0
	v_pk_mul_f32 v[6:7], v[14:15], v[10:11]
	s_nop 0
	v_pk_mul_f32 v[10:11], v[4:5], v[6:7]
	v_cvt_pk_bf16_f32 v5, v8, v9
	v_lshl_add_u64 v[8:9], s[12:13], 0, v[16:17]
	v_cvt_pk_bf16_f32 v4, v20, v21
	v_cvt_pk_bf16_f32 v6, v12, v13
	v_cvt_pk_bf16_f32 v7, v10, v11
	v_lshl_add_u64 v[8:9], v[8:9], 0, v[18:19]
	global_store_dwordx4 v[8:9], v[4:7], off
	s_add_i32 s19, s19, -1
	s_cmp_lg_u32 s19, 0
	s_cbranch_scc1 .LBB0_363
	s_add_i32 s17, s17, s74
	s_cmpk_lt_i32 s17, 0x100
	s_cbranch_scc1 .Lgate_bun
